# v30 + indexer-score MFMA loop: all eight query-fragment LDS reads of an iteration issued at its top behind counted waits (four loop copies)
# speedup vs baseline: 1.0027x; 1.0014x over previous
; #define LAS __attribute__((address_space(3)))
; __device__ __forceinline__ void score_item(const Frame& F, int l, int samp, int b, int c, int kc) {
;     ...
;             for (int hh = 0; hh < 8; hh += 2) {
;                 f32x16 s0, s1;
; #pragma unroll
;                 for (int i = 0; i < 16; ++i) { s0[i] = 0.f; s1[i] = 0.f; }
; #pragma unroll
;                 for (int ks = 0; ks < 4; ++ks) { const LAS unsigned char* ap = QiL + (32 * qh + rl) * 1040 + (hh * 64 + 16 * ks + 8 * h) * 2;
;                     const bf16x8 a0 = *(const LAS bf16x8*)(ap), a1 = *(const LAS bf16x8*)(ap + 128);
;                     s0 = __builtin_amdgcn_mfma_f32_32x32x16_bf16(a0, bfr[ks], s0, 0, 0, 0); s1 = __builtin_amdgcn_mfma_f32_32x32x16_bf16(a1, bfr[ks], s1, 0, 0, 0); }
; #pragma unroll
;                 for (int i = 0; i < 16; ++i) { const int q = 32 * qh + (i & 3) + 8 * (i >> 2) + 4 * h; const f32x2 w2 = *(const LAS f32x2*)(WIl + q * 8 + hh); sc[i] += w2[0] * fmaxf(s0[i], 0.f) + w2[1] * fmaxf(s1[i], 0.f); }
;             }
.LBB0_850:
	v_add_u32_e32 v107, 0, v106
	ds_read_b128 v[0:3], v107 offset:128
	ds_read_b128 v[4:7], v107
	ds_read_b128 v[108:111], v107 offset:32
	ds_read_b128 v[112:115], v107 offset:160
	ds_read_b128 v[126:129], v107 offset:64
	ds_read_b128 v[130:133], v107 offset:192
	ds_read_b128 v[134:137], v107 offset:96
	ds_read_b128 v[138:141], v107 offset:224
	s_add_i32 s11, s11, 2
	v_add_u32_e32 v106, 0x100, v106
	s_waitcnt lgkmcnt(6)
	v_mfma_f32_32x32x16_bf16 v[16:31], v[4:7], v[48:51], 0
	s_cmp_gt_u32 s11, 5
	v_mfma_f32_32x32x16_bf16 v[0:15], v[0:3], v[48:51], 0
	s_waitcnt lgkmcnt(4)
	v_mfma_f32_32x32x16_bf16 v[0:15], v[112:115], v[52:55], v[0:15]
	v_mfma_f32_32x32x16_bf16 v[16:31], v[108:111], v[52:55], v[16:31]
	s_waitcnt lgkmcnt(2)
	v_mfma_f32_32x32x16_bf16 v[0:15], v[130:133], v[56:59], v[0:15]
	v_mfma_f32_32x32x16_bf16 v[16:31], v[126:129], v[56:59], v[16:31]
	v_add_u32_e32 v107, 0, v105
	v_add_u32_e32 v105, 8, v105
	s_waitcnt lgkmcnt(0)
	v_mfma_f32_32x32x16_bf16 v[0:15], v[138:141], v[60:63], v[0:15]
	v_mfma_f32_32x32x16_bf16 v[16:31], v[134:137], v[60:63], v[16:31]
	v_add_u32_e32 v108, 0x10400, v107
	v_add_u32_e32 v110, 0x10420, v107
	ds_read_b64 v[108:109], v108
	ds_read_b64 v[110:111], v110
	s_nop 6
	v_max_f32_e32 v0, v0, v0
	v_max_f32_e32 v1, v1, v1
	v_max_f32_e32 v0, 0, v0
	v_max_f32_e32 v16, v16, v16
	v_max_f32_e32 v17, v17, v17
	v_max_f32_e32 v1, 0, v1
	s_waitcnt lgkmcnt(0)
	v_mov_b32_e32 v113, v110
	v_mov_b32_e32 v110, v109
	v_max_f32_e32 v16, 0, v16
	v_max_f32_e32 v17, 0, v17
	v_mov_b32_e32 v112, v108
	v_pk_mul_f32 v[0:1], v[0:1], v[110:111]
	v_max_f32_e32 v2, v2, v2
	v_pk_fma_f32 v[0:1], v[16:17], v[112:113], v[0:1]
	v_add_u32_e32 v17, 0x10460, v107
	v_pk_add_f32 v[100:101], v[100:101], v[0:1]
	v_add_u32_e32 v0, 0x10440, v107
	ds_read_b64 v[0:1], v0
	ds_read_b64 v[108:109], v17
	v_max_f32_e32 v3, v3, v3
	v_max_f32_e32 v16, v18, v18
	v_max_f32_e32 v2, 0, v2
	v_max_f32_e32 v17, v19, v19
	v_max_f32_e32 v3, 0, v3
	s_waitcnt lgkmcnt(0)
	v_mov_b32_e32 v19, v108
	v_mov_b32_e32 v108, v1
	v_max_f32_e32 v16, 0, v16
	v_max_f32_e32 v17, 0, v17
	v_mov_b32_e32 v18, v0
	v_pk_mul_f32 v[0:1], v[2:3], v[108:109]
	v_max_f32_e32 v3, v4, v4
	v_pk_fma_f32 v[0:1], v[16:17], v[18:19], v[0:1]
	v_max_f32_e32 v4, 0, v3
	v_pk_add_f32 v[98:99], v[98:99], v[0:1]
	v_add_u32_e32 v0, 0x10500, v107
	v_add_u32_e32 v3, 0x10520, v107
	ds_read_b64 v[0:1], v0
	ds_read_b64 v[16:17], v3
	v_max_f32_e32 v5, v5, v5
	v_max_f32_e32 v2, v20, v20
	v_max_f32_e32 v3, v21, v21
	v_max_f32_e32 v5, 0, v5
	s_waitcnt lgkmcnt(0)
	v_mov_b32_e32 v19, v16
	v_mov_b32_e32 v16, v1
	v_max_f32_e32 v2, 0, v2
	v_max_f32_e32 v3, 0, v3
	v_mov_b32_e32 v18, v0
	v_pk_mul_f32 v[0:1], v[4:5], v[16:17]
	v_max_f32_e32 v5, v7, v7
	v_pk_fma_f32 v[0:1], v[2:3], v[18:19], v[0:1]
	v_max_f32_e32 v3, v6, v6
	v_pk_add_f32 v[96:97], v[96:97], v[0:1]
	v_add_u32_e32 v0, 0x10540, v107
	v_max_f32_e32 v4, 0, v3
	v_add_u32_e32 v3, 0x10560, v107
	ds_read_b64 v[0:1], v0
	ds_read_b64 v[16:17], v3
	v_max_f32_e32 v2, v22, v22
	v_max_f32_e32 v3, v23, v23
	v_max_f32_e32 v5, 0, v5
	v_max_f32_e32 v2, 0, v2
	s_waitcnt lgkmcnt(0)
	v_mov_b32_e32 v7, v16
	v_mov_b32_e32 v16, v1
	v_max_f32_e32 v3, 0, v3
	v_mov_b32_e32 v6, v0
	v_pk_mul_f32 v[0:1], v[4:5], v[16:17]
	v_max_f32_e32 v5, v9, v9
	v_pk_fma_f32 v[0:1], v[2:3], v[6:7], v[0:1]
	v_max_f32_e32 v3, v8, v8
	v_pk_add_f32 v[94:95], v[94:95], v[0:1]
	v_add_u32_e32 v0, 0x10600, v107
	v_max_f32_e32 v4, 0, v3
	v_add_u32_e32 v3, 0x10620, v107
	ds_read_b64 v[0:1], v0
	ds_read_b64 v[6:7], v3
	v_max_f32_e32 v2, v24, v24
	v_max_f32_e32 v3, v25, v25
	v_max_f32_e32 v5, 0, v5
	v_max_f32_e32 v2, 0, v2
	s_waitcnt lgkmcnt(0)
	v_mov_b32_e32 v9, v6
	v_mov_b32_e32 v6, v1
	v_max_f32_e32 v3, 0, v3
	v_mov_b32_e32 v8, v0
	v_pk_mul_f32 v[0:1], v[4:5], v[6:7]
	v_max_f32_e32 v5, v11, v11
	v_pk_fma_f32 v[0:1], v[2:3], v[8:9], v[0:1]
	v_max_f32_e32 v3, v10, v10
	v_pk_add_f32 v[92:93], v[92:93], v[0:1]
	v_add_u32_e32 v0, 0x10640, v107
	v_max_f32_e32 v4, 0, v3
	v_add_u32_e32 v3, 0x10660, v107
	ds_read_b64 v[0:1], v0
	ds_read_b64 v[6:7], v3
	v_max_f32_e32 v2, v26, v26
	v_max_f32_e32 v3, v27, v27
	v_max_f32_e32 v5, 0, v5
	v_max_f32_e32 v2, 0, v2
	s_waitcnt lgkmcnt(0)
	v_mov_b32_e32 v9, v6
	v_mov_b32_e32 v6, v1
	v_max_f32_e32 v3, 0, v3
	v_mov_b32_e32 v8, v0
	v_pk_mul_f32 v[0:1], v[4:5], v[6:7]
	v_max_f32_e32 v5, v13, v13
	v_pk_fma_f32 v[0:1], v[2:3], v[8:9], v[0:1]
	v_max_f32_e32 v3, v12, v12
	v_pk_add_f32 v[90:91], v[90:91], v[0:1]
	v_add_u32_e32 v0, 0x10700, v107
	v_max_f32_e32 v4, 0, v3
	v_add_u32_e32 v3, 0x10720, v107
	ds_read_b64 v[0:1], v0
	ds_read_b64 v[6:7], v3
	v_max_f32_e32 v2, v28, v28
	v_max_f32_e32 v3, v29, v29
	v_max_f32_e32 v5, 0, v5
	v_max_f32_e32 v2, 0, v2
	s_waitcnt lgkmcnt(0)
	v_mov_b32_e32 v9, v6
	v_mov_b32_e32 v6, v1
	v_max_f32_e32 v3, 0, v3
	v_mov_b32_e32 v8, v0
	v_pk_mul_f32 v[0:1], v[4:5], v[6:7]
	s_nop 0
	v_pk_fma_f32 v[0:1], v[2:3], v[8:9], v[0:1]
	v_max_f32_e32 v2, v30, v30
	v_pk_add_f32 v[88:89], v[88:89], v[0:1]
	v_add_u32_e32 v0, 0x10740, v107
	ds_read_b64 v[0:1], v0
	v_max_f32_e32 v2, 0, v2
	s_waitcnt lgkmcnt(0)
	v_mul_f32_e32 v0, v2, v0
	v_max_f32_e32 v2, v14, v14
	v_max_f32_e32 v2, 0, v2
	v_mul_f32_e32 v2, v2, v1
	v_add_u32_e32 v1, 0x10760, v107
	ds_read_b64 v[4:5], v1
	v_max_f32_e32 v1, v31, v31
	v_max_f32_e32 v6, 0, v1
	v_max_f32_e32 v1, v15, v15
	v_max_f32_e32 v7, 0, v1
	s_waitcnt lgkmcnt(0)
	v_pk_mul_f32 v[4:5], v[6:7], v[4:5]
	s_nop 0
	v_mov_b32_e32 v1, v4
	v_mov_b32_e32 v3, v5
	v_pk_add_f32 v[0:1], v[0:1], v[2:3]
	s_nop 0
	v_pk_add_f32 v[86:87], v[86:87], v[0:1]
	s_cbranch_scc0 .LBB0_850
; __device__ __forceinline__ void score_item(const Frame& F, int l, int samp, int b, int c, int kc) {
;     ...
; #pragma unroll
;             for (int i = 0; i < 16; ++i) { const int q = 32 * qh + (i & 3) + 8 * (i >> 2) + 4 * h; __hip_atomic_store(SC + (size_t)q * 4096 + key, __float_as_uint(sc[i]), __ATOMIC_RELAXED, __HIP_MEMORY_SCOPE_AGENT); }
	v_add_u32_e32 v0, s10, v103
	v_or_b32_e32 v4, 1, v0
	v_ashrrev_i32_e32 v1, 31, v0
	v_ashrrev_i32_e32 v5, 31, v4
	v_lshlrev_b64 v[2:3], 14, v[0:1]
	v_lshlrev_b64 v[4:5], 14, v[4:5]
	v_lshl_add_u64 v[2:3], v[84:85], 0, v[2:3]
	v_lshl_add_u64 v[4:5], v[84:85], 0, v[4:5]
	global_store_dword v[2:3], v100, off sc1
	global_store_dword v[4:5], v101, off sc1
	v_or_b32_e32 v4, 2, v0
	v_or_b32_e32 v0, 3, v0
	v_ashrrev_i32_e32 v5, 31, v4
	v_ashrrev_i32_e32 v1, 31, v0
	v_lshlrev_b64 v[4:5], 14, v[4:5]
	v_lshlrev_b64 v[0:1], 14, v[0:1]
	v_lshl_add_u64 v[4:5], v[84:85], 0, v[4:5]
	v_lshl_add_u64 v[0:1], v[84:85], 0, v[0:1]
	global_store_dword v[4:5], v98, off sc1
	global_store_dword v[0:1], v99, off sc1
	v_add_co_u32_e32 v0, vcc, s92, v2
	s_mov_b32 s14, 1
	s_nop 0
	v_addc_co_u32_e32 v1, vcc, 0, v3, vcc
	global_store_dword v[0:1], v96, off sc1
	v_add_co_u32_e32 v0, vcc, s77, v2
	s_mov_b64 s[10:11], 0
	s_nop 0
	v_addc_co_u32_e32 v1, vcc, 0, v3, vcc
	global_store_dword v[0:1], v97, off sc1
	v_add_co_u32_e32 v0, vcc, s76, v2
	s_nop 1
	v_addc_co_u32_e32 v1, vcc, 0, v3, vcc
	global_store_dword v[0:1], v94, off sc1
	v_add_co_u32_e32 v0, vcc, s78, v2
	s_nop 1
	v_addc_co_u32_e32 v1, vcc, 0, v3, vcc
	global_store_dword v[0:1], v95, off sc1
	v_add_co_u32_e32 v0, vcc, s82, v2
	s_nop 1
	v_addc_co_u32_e32 v1, vcc, 0, v3, vcc
	global_store_dword v[0:1], v92, off sc1
	v_add_co_u32_e32 v0, vcc, s31, v2
	s_nop 1
	v_addc_co_u32_e32 v1, vcc, 0, v3, vcc
	global_store_dword v[0:1], v93, off sc1
	v_add_co_u32_e32 v0, vcc, s84, v2
	s_nop 1
	v_addc_co_u32_e32 v1, vcc, 0, v3, vcc
	global_store_dword v[0:1], v90, off sc1
	v_add_co_u32_e32 v0, vcc, 0x4c000, v2
	s_nop 1
	v_addc_co_u32_e32 v1, vcc, 0, v3, vcc
	global_store_dword v[0:1], v91, off sc1
	v_add_co_u32_e32 v0, vcc, s83, v2
	s_nop 1
	v_addc_co_u32_e32 v1, vcc, 0, v3, vcc
	global_store_dword v[0:1], v88, off sc1
	v_add_co_u32_e32 v0, vcc, 0x64000, v2
	s_nop 1
	v_addc_co_u32_e32 v1, vcc, 0, v3, vcc
	global_store_dword v[0:1], v89, off sc1
	v_add_co_u32_e32 v0, vcc, 0x68000, v2
	s_nop 1
	v_addc_co_u32_e32 v1, vcc, 0, v3, vcc
	global_store_dword v[0:1], v86, off sc1
	v_add_co_u32_e32 v0, vcc, 0x6c000, v2
	s_nop 1
	v_addc_co_u32_e32 v1, vcc, 0, v3, vcc
	s_and_b64 vcc, exec, s[8:9]
	global_store_dword v[0:1], v87, off sc1
	s_cbranch_vccz .LBB0_849

; #define LAS __attribute__((address_space(3)))
; __device__ __forceinline__ void score_item(const Frame& F, int l, int samp, int b, int c, int kc) {
;     ...
;             for (int hh = 0; hh < 8; hh += 2) {
;                 f32x16 s0, s1;
; #pragma unroll
;                 for (int i = 0; i < 16; ++i) { s0[i] = 0.f; s1[i] = 0.f; }
; #pragma unroll
;                 for (int ks = 0; ks < 4; ++ks) { const LAS unsigned char* ap = QiL + (32 * qh + rl) * 1040 + (hh * 64 + 16 * ks + 8 * h) * 2;
;                     const bf16x8 a0 = *(const LAS bf16x8*)(ap), a1 = *(const LAS bf16x8*)(ap + 128);
;                     s0 = __builtin_amdgcn_mfma_f32_32x32x16_bf16(a0, bfr[ks], s0, 0, 0, 0); s1 = __builtin_amdgcn_mfma_f32_32x32x16_bf16(a1, bfr[ks], s1, 0, 0, 0); }
; #pragma unroll
;                 for (int i = 0; i < 16; ++i) { const int q = 32 * qh + (i & 3) + 8 * (i >> 2) + 4 * h; const f32x2 w2 = *(const LAS f32x2*)(WIl + q * 8 + hh); sc[i] += w2[0] * fmaxf(s0[i], 0.f) + w2[1] * fmaxf(s1[i], 0.f); }
;             }
.LBB0_857:
	v_add_u32_e32 v69, 0, v68
	ds_read_b128 v[0:3], v69 offset:128
	ds_read_b128 v[4:7], v69
	ds_read_b128 v[70:73], v69 offset:32
	ds_read_b128 v[74:77], v69 offset:160
	ds_read_b128 v[126:129], v69 offset:64
	ds_read_b128 v[130:133], v69 offset:192
	ds_read_b128 v[134:137], v69 offset:96
	ds_read_b128 v[138:141], v69 offset:224
	s_add_i32 s7, s7, 2
	v_add_u32_e32 v68, 0x100, v68
	s_waitcnt lgkmcnt(6)
	v_mfma_f32_32x32x16_bf16 v[16:31], v[4:7], v[32:35], 0
	s_cmp_lt_u32 s7, 6
	v_mfma_f32_32x32x16_bf16 v[0:15], v[0:3], v[32:35], 0
	s_waitcnt lgkmcnt(4)
	v_mfma_f32_32x32x16_bf16 v[0:15], v[74:77], v[36:39], v[0:15]
	v_mfma_f32_32x32x16_bf16 v[16:31], v[70:73], v[36:39], v[16:31]
	s_waitcnt lgkmcnt(2)
	v_mfma_f32_32x32x16_bf16 v[0:15], v[130:133], v[40:43], v[0:15]
	v_mfma_f32_32x32x16_bf16 v[16:31], v[126:129], v[40:43], v[16:31]
	v_add_u32_e32 v69, 0, v67
	v_add_u32_e32 v67, 8, v67
	s_waitcnt lgkmcnt(0)
	v_mfma_f32_32x32x16_bf16 v[0:15], v[138:141], v[44:47], v[0:15]
	v_mfma_f32_32x32x16_bf16 v[16:31], v[134:137], v[44:47], v[16:31]
	v_add_u32_e32 v70, 0x10400, v69
	v_add_u32_e32 v72, 0x10420, v69
	ds_read_b64 v[70:71], v70
	ds_read_b64 v[72:73], v72
	s_nop 6
	v_max_f32_e32 v0, v0, v0
	v_max_f32_e32 v1, v1, v1
	v_max_f32_e32 v0, 0, v0
	v_max_f32_e32 v16, v16, v16
	v_max_f32_e32 v17, v17, v17
	v_max_f32_e32 v1, 0, v1
	s_waitcnt lgkmcnt(0)
	v_mov_b32_e32 v75, v72
	v_mov_b32_e32 v72, v71
	v_max_f32_e32 v16, 0, v16
	v_max_f32_e32 v17, 0, v17
	v_mov_b32_e32 v74, v70
	v_pk_mul_f32 v[0:1], v[0:1], v[72:73]
	v_max_f32_e32 v2, v2, v2
	v_pk_fma_f32 v[0:1], v[16:17], v[74:75], v[0:1]
	v_add_u32_e32 v17, 0x10460, v69
	v_pk_add_f32 v[64:65], v[64:65], v[0:1]
	v_add_u32_e32 v0, 0x10440, v69
	ds_read_b64 v[0:1], v0
	ds_read_b64 v[70:71], v17
	v_max_f32_e32 v3, v3, v3
	v_max_f32_e32 v16, v18, v18
	v_max_f32_e32 v2, 0, v2
	v_max_f32_e32 v17, v19, v19
	v_max_f32_e32 v3, 0, v3
	s_waitcnt lgkmcnt(0)
	v_mov_b32_e32 v19, v70
	v_mov_b32_e32 v70, v1
	v_max_f32_e32 v16, 0, v16
	v_max_f32_e32 v17, 0, v17
	v_mov_b32_e32 v18, v0
	v_pk_mul_f32 v[0:1], v[2:3], v[70:71]
	v_max_f32_e32 v3, v4, v4
	v_pk_fma_f32 v[0:1], v[16:17], v[18:19], v[0:1]
	v_max_f32_e32 v4, 0, v3
	v_pk_add_f32 v[62:63], v[62:63], v[0:1]
	v_add_u32_e32 v0, 0x10500, v69
	v_add_u32_e32 v3, 0x10520, v69
	ds_read_b64 v[0:1], v0
	ds_read_b64 v[16:17], v3
	v_max_f32_e32 v5, v5, v5
	v_max_f32_e32 v2, v20, v20
	v_max_f32_e32 v3, v21, v21
	v_max_f32_e32 v5, 0, v5
	s_waitcnt lgkmcnt(0)
	v_mov_b32_e32 v19, v16
	v_mov_b32_e32 v16, v1
	v_max_f32_e32 v2, 0, v2
	v_max_f32_e32 v3, 0, v3
	v_mov_b32_e32 v18, v0
	v_pk_mul_f32 v[0:1], v[4:5], v[16:17]
	v_max_f32_e32 v5, v7, v7
	v_pk_fma_f32 v[0:1], v[2:3], v[18:19], v[0:1]
	v_max_f32_e32 v3, v6, v6
	v_pk_add_f32 v[60:61], v[60:61], v[0:1]
	v_add_u32_e32 v0, 0x10540, v69
	v_max_f32_e32 v4, 0, v3
	v_add_u32_e32 v3, 0x10560, v69
	ds_read_b64 v[0:1], v0
	ds_read_b64 v[16:17], v3
	v_max_f32_e32 v2, v22, v22
	v_max_f32_e32 v3, v23, v23
	v_max_f32_e32 v5, 0, v5
	v_max_f32_e32 v2, 0, v2
	s_waitcnt lgkmcnt(0)
	v_mov_b32_e32 v7, v16
	v_mov_b32_e32 v16, v1
	v_max_f32_e32 v3, 0, v3
	v_mov_b32_e32 v6, v0
	v_pk_mul_f32 v[0:1], v[4:5], v[16:17]
	v_max_f32_e32 v5, v9, v9
	v_pk_fma_f32 v[0:1], v[2:3], v[6:7], v[0:1]
	v_max_f32_e32 v3, v8, v8
	v_pk_add_f32 v[58:59], v[58:59], v[0:1]
	v_add_u32_e32 v0, 0x10600, v69
	v_max_f32_e32 v4, 0, v3
	v_add_u32_e32 v3, 0x10620, v69
	ds_read_b64 v[0:1], v0
	ds_read_b64 v[6:7], v3
	v_max_f32_e32 v2, v24, v24
	v_max_f32_e32 v3, v25, v25
	v_max_f32_e32 v5, 0, v5
	v_max_f32_e32 v2, 0, v2
	s_waitcnt lgkmcnt(0)
	v_mov_b32_e32 v9, v6
	v_mov_b32_e32 v6, v1
	v_max_f32_e32 v3, 0, v3
	v_mov_b32_e32 v8, v0
	v_pk_mul_f32 v[0:1], v[4:5], v[6:7]
	v_max_f32_e32 v5, v11, v11
	v_pk_fma_f32 v[0:1], v[2:3], v[8:9], v[0:1]
	v_max_f32_e32 v3, v10, v10
	v_pk_add_f32 v[56:57], v[56:57], v[0:1]
	v_add_u32_e32 v0, 0x10640, v69
	v_max_f32_e32 v4, 0, v3
	v_add_u32_e32 v3, 0x10660, v69
	ds_read_b64 v[0:1], v0
	ds_read_b64 v[6:7], v3
	v_max_f32_e32 v2, v26, v26
	v_max_f32_e32 v3, v27, v27
	v_max_f32_e32 v5, 0, v5
	v_max_f32_e32 v2, 0, v2
	s_waitcnt lgkmcnt(0)
	v_mov_b32_e32 v9, v6
	v_mov_b32_e32 v6, v1
	v_max_f32_e32 v3, 0, v3
	v_mov_b32_e32 v8, v0
	v_pk_mul_f32 v[0:1], v[4:5], v[6:7]
	v_max_f32_e32 v5, v13, v13
	v_pk_fma_f32 v[0:1], v[2:3], v[8:9], v[0:1]
	v_max_f32_e32 v3, v12, v12
	v_pk_add_f32 v[54:55], v[54:55], v[0:1]
	v_add_u32_e32 v0, 0x10700, v69
	v_max_f32_e32 v4, 0, v3
	v_add_u32_e32 v3, 0x10720, v69
	ds_read_b64 v[0:1], v0
	ds_read_b64 v[6:7], v3
	v_max_f32_e32 v2, v28, v28
	v_max_f32_e32 v3, v29, v29
	v_max_f32_e32 v5, 0, v5
	v_max_f32_e32 v2, 0, v2
	s_waitcnt lgkmcnt(0)
	v_mov_b32_e32 v9, v6
	v_mov_b32_e32 v6, v1
	v_max_f32_e32 v3, 0, v3
	v_mov_b32_e32 v8, v0
	v_pk_mul_f32 v[0:1], v[4:5], v[6:7]
	s_nop 0
	v_pk_fma_f32 v[0:1], v[2:3], v[8:9], v[0:1]
	v_max_f32_e32 v2, v30, v30
	v_pk_add_f32 v[52:53], v[52:53], v[0:1]
	v_add_u32_e32 v0, 0x10740, v69
	ds_read_b64 v[0:1], v0
	v_max_f32_e32 v2, 0, v2
	s_waitcnt lgkmcnt(0)
	v_mul_f32_e32 v0, v2, v0
	v_max_f32_e32 v2, v14, v14
	v_max_f32_e32 v2, 0, v2
	v_mul_f32_e32 v2, v2, v1
	v_add_u32_e32 v1, 0x10760, v69
	ds_read_b64 v[4:5], v1
	v_max_f32_e32 v1, v31, v31
	v_max_f32_e32 v6, 0, v1
	v_max_f32_e32 v1, v15, v15
	v_max_f32_e32 v7, 0, v1
	s_waitcnt lgkmcnt(0)
	v_pk_mul_f32 v[4:5], v[6:7], v[4:5]
	s_nop 0
	v_mov_b32_e32 v1, v4
	v_mov_b32_e32 v3, v5
	v_pk_add_f32 v[0:1], v[0:1], v[2:3]
	s_nop 0
	v_pk_add_f32 v[50:51], v[50:51], v[0:1]
	s_cbranch_scc1 .LBB0_857
; __device__ __forceinline__ void score_item(const Frame& F, int l, int samp, int b, int c, int kc) {
;     ...
; #pragma unroll
;             for (int i = 0; i < 16; ++i) { const int q = 32 * qh + (i & 3) + 8 * (i >> 2) + 4 * h; __hip_atomic_store(SC + (size_t)q * 4096 + key, __float_as_uint(sc[i]), __ATOMIC_RELAXED, __HIP_MEMORY_SCOPE_AGENT); }
	v_add_u32_e32 v0, s6, v103
	v_or_b32_e32 v4, 1, v0
	v_ashrrev_i32_e32 v1, 31, v0
	v_ashrrev_i32_e32 v5, 31, v4
	v_lshlrev_b64 v[2:3], 14, v[0:1]
	v_lshlrev_b64 v[4:5], 14, v[4:5]
	v_lshl_add_u64 v[2:3], v[48:49], 0, v[2:3]
	v_lshl_add_u64 v[4:5], v[48:49], 0, v[4:5]
	global_store_dword v[2:3], v64, off sc1
	global_store_dword v[4:5], v65, off sc1
	v_or_b32_e32 v4, 2, v0
	v_or_b32_e32 v0, 3, v0
	v_ashrrev_i32_e32 v5, 31, v4
	v_ashrrev_i32_e32 v1, 31, v0
	v_lshlrev_b64 v[4:5], 14, v[4:5]
	v_lshlrev_b64 v[0:1], 14, v[0:1]
	v_lshl_add_u64 v[4:5], v[48:49], 0, v[4:5]
	v_lshl_add_u64 v[0:1], v[48:49], 0, v[0:1]
	global_store_dword v[4:5], v62, off sc1
	global_store_dword v[0:1], v63, off sc1
	v_add_co_u32_e32 v0, vcc, s92, v2
	s_mov_b32 s7, 1
	s_nop 0
	v_addc_co_u32_e32 v1, vcc, 0, v3, vcc
	global_store_dword v[0:1], v60, off sc1
	v_add_co_u32_e32 v0, vcc, s77, v2
	s_nop 1
	v_addc_co_u32_e32 v1, vcc, 0, v3, vcc
	global_store_dword v[0:1], v61, off sc1
	v_add_co_u32_e32 v0, vcc, s76, v2
	s_nop 1
	v_addc_co_u32_e32 v1, vcc, 0, v3, vcc
	global_store_dword v[0:1], v58, off sc1
	v_add_co_u32_e32 v0, vcc, s78, v2
	s_nop 1
	v_addc_co_u32_e32 v1, vcc, 0, v3, vcc
	global_store_dword v[0:1], v59, off sc1
	v_add_co_u32_e32 v0, vcc, s82, v2
	s_nop 1
	v_addc_co_u32_e32 v1, vcc, 0, v3, vcc
	global_store_dword v[0:1], v56, off sc1
	v_add_co_u32_e32 v0, vcc, s31, v2
	s_nop 1
	v_addc_co_u32_e32 v1, vcc, 0, v3, vcc
	global_store_dword v[0:1], v57, off sc1
	v_add_co_u32_e32 v0, vcc, s84, v2
	s_nop 1
	v_addc_co_u32_e32 v1, vcc, 0, v3, vcc
	global_store_dword v[0:1], v54, off sc1
	v_add_co_u32_e32 v0, vcc, 0x4c000, v2
	s_nop 1
	v_addc_co_u32_e32 v1, vcc, 0, v3, vcc
	global_store_dword v[0:1], v55, off sc1
	v_add_co_u32_e32 v0, vcc, s83, v2
	s_nop 1
	v_addc_co_u32_e32 v1, vcc, 0, v3, vcc
	global_store_dword v[0:1], v52, off sc1
	v_add_co_u32_e32 v0, vcc, 0x64000, v2
	s_nop 1
	v_addc_co_u32_e32 v1, vcc, 0, v3, vcc
	global_store_dword v[0:1], v53, off sc1
	v_add_co_u32_e32 v0, vcc, 0x68000, v2
	s_nop 1
	v_addc_co_u32_e32 v1, vcc, 0, v3, vcc
	global_store_dword v[0:1], v50, off sc1
	v_add_co_u32_e32 v0, vcc, 0x6c000, v2
	s_nop 1
	v_addc_co_u32_e32 v1, vcc, 0, v3, vcc
	s_andn2_b64 vcc, exec, s[4:5]
	s_mov_b64 s[4:5], 0
	global_store_dword v[0:1], v51, off sc1
	s_cbranch_vccnz .LBB0_856

; #define LAS __attribute__((address_space(3)))
; __device__ __forceinline__ void score_item(const Frame& F, int l, int samp, int b, int c, int kc) {
;     ...
;             for (int hh = 0; hh < 8; hh += 2) {
;                 f32x16 s0, s1;
; #pragma unroll
;                 for (int i = 0; i < 16; ++i) { s0[i] = 0.f; s1[i] = 0.f; }
; #pragma unroll
;                 for (int ks = 0; ks < 4; ++ks) { const LAS unsigned char* ap = QiL + (32 * qh + rl) * 1040 + (hh * 64 + 16 * ks + 8 * h) * 2;
;                     const bf16x8 a0 = *(const LAS bf16x8*)(ap), a1 = *(const LAS bf16x8*)(ap + 128);
;                     s0 = __builtin_amdgcn_mfma_f32_32x32x16_bf16(a0, bfr[ks], s0, 0, 0, 0); s1 = __builtin_amdgcn_mfma_f32_32x32x16_bf16(a1, bfr[ks], s1, 0, 0, 0); }
; #pragma unroll
;                 for (int i = 0; i < 16; ++i) { const int q = 32 * qh + (i & 3) + 8 * (i >> 2) + 4 * h; const f32x2 w2 = *(const LAS f32x2*)(WIl + q * 8 + hh); sc[i] += w2[0] * fmaxf(s0[i], 0.f) + w2[1] * fmaxf(s1[i], 0.f); }
;             }
.LBB0_872:
	v_add_u32_e32 v98, 0, v89
	ds_read_b128 v[0:3], v98 offset:128
	ds_read_b128 v[4:7], v98
	ds_read_b128 v[90:93], v98 offset:32
	ds_read_b128 v[94:97], v98 offset:160
	ds_read_b128 v[126:129], v98 offset:64
	ds_read_b128 v[130:133], v98 offset:192
	ds_read_b128 v[134:137], v98 offset:96
	ds_read_b128 v[138:141], v98 offset:224
	s_add_i32 s14, s14, 2
	v_add_u32_e32 v89, 0x100, v89
	s_waitcnt lgkmcnt(6)
	v_mfma_f32_32x32x16_bf16 v[16:31], v[4:7], v[60:63], 0
	s_cmp_gt_u32 s14, 5
	v_mfma_f32_32x32x16_bf16 v[0:15], v[0:3], v[60:63], 0
	s_waitcnt lgkmcnt(4)
	v_mfma_f32_32x32x16_bf16 v[0:15], v[94:97], v[56:59], v[0:15]
	v_mfma_f32_32x32x16_bf16 v[16:31], v[90:93], v[56:59], v[16:31]
	s_waitcnt lgkmcnt(2)
	v_mfma_f32_32x32x16_bf16 v[0:15], v[130:133], v[52:55], v[0:15]
	v_mfma_f32_32x32x16_bf16 v[16:31], v[126:129], v[52:55], v[16:31]
	s_waitcnt lgkmcnt(0)
	v_mfma_f32_32x32x16_bf16 v[0:15], v[138:141], v[48:51], v[0:15]
	v_add_u32_e32 v96, 0, v67
	v_add_u32_e32 v67, 8, v67
	v_mfma_f32_32x32x16_bf16 v[16:31], v[134:137], v[48:51], v[16:31]
	v_add_u32_e32 v90, 0x10400, v96
	v_add_u32_e32 v92, 0x10420, v96
	ds_read_b64 v[90:91], v90
	ds_read_b64 v[92:93], v92
	s_nop 4
	v_max_f32_e32 v0, v0, v0
	v_max_f32_e32 v1, v1, v1
	v_max_f32_e32 v0, 0, v0
	v_max_f32_e32 v16, v16, v16
	v_max_f32_e32 v17, v17, v17
	v_max_f32_e32 v1, 0, v1
	s_waitcnt lgkmcnt(0)
	v_mov_b32_e32 v95, v92
	v_mov_b32_e32 v92, v91
	v_max_f32_e32 v16, 0, v16
	v_max_f32_e32 v17, 0, v17
	v_mov_b32_e32 v94, v90
	v_pk_mul_f32 v[0:1], v[0:1], v[92:93]
	v_max_f32_e32 v2, v2, v2
	v_pk_fma_f32 v[0:1], v[16:17], v[94:95], v[0:1]
	v_add_u32_e32 v17, 0x10460, v96
	v_pk_add_f32 v[84:85], v[84:85], v[0:1]
	v_add_u32_e32 v0, 0x10440, v96
	ds_read_b64 v[0:1], v0
	ds_read_b64 v[90:91], v17
	v_max_f32_e32 v3, v3, v3
	v_max_f32_e32 v16, v18, v18
	v_max_f32_e32 v2, 0, v2
	v_max_f32_e32 v17, v19, v19
	v_max_f32_e32 v3, 0, v3
	s_waitcnt lgkmcnt(0)
	v_mov_b32_e32 v19, v90
	v_mov_b32_e32 v90, v1
	v_max_f32_e32 v16, 0, v16
	v_max_f32_e32 v17, 0, v17
	v_mov_b32_e32 v18, v0
	v_pk_mul_f32 v[0:1], v[2:3], v[90:91]
	v_max_f32_e32 v3, v4, v4
	v_pk_fma_f32 v[0:1], v[16:17], v[18:19], v[0:1]
	v_max_f32_e32 v4, 0, v3
	v_pk_add_f32 v[82:83], v[82:83], v[0:1]
	v_add_u32_e32 v0, 0x10500, v96
	v_add_u32_e32 v3, 0x10520, v96
	ds_read_b64 v[0:1], v0
	ds_read_b64 v[16:17], v3
	v_max_f32_e32 v5, v5, v5
	v_max_f32_e32 v2, v20, v20
	v_max_f32_e32 v3, v21, v21
	v_max_f32_e32 v5, 0, v5
	s_waitcnt lgkmcnt(0)
	v_mov_b32_e32 v19, v16
	v_mov_b32_e32 v16, v1
	v_max_f32_e32 v2, 0, v2
	v_max_f32_e32 v3, 0, v3
	v_mov_b32_e32 v18, v0
	v_pk_mul_f32 v[0:1], v[4:5], v[16:17]
	v_max_f32_e32 v5, v7, v7
	v_pk_fma_f32 v[0:1], v[2:3], v[18:19], v[0:1]
	v_max_f32_e32 v3, v6, v6
	v_pk_add_f32 v[80:81], v[80:81], v[0:1]
	v_add_u32_e32 v0, 0x10540, v96
	v_max_f32_e32 v4, 0, v3
	v_add_u32_e32 v3, 0x10560, v96
	ds_read_b64 v[0:1], v0
	ds_read_b64 v[16:17], v3
	v_max_f32_e32 v2, v22, v22
	v_max_f32_e32 v3, v23, v23
	v_max_f32_e32 v5, 0, v5
	v_max_f32_e32 v2, 0, v2
	s_waitcnt lgkmcnt(0)
	v_mov_b32_e32 v7, v16
	v_mov_b32_e32 v16, v1
	v_max_f32_e32 v3, 0, v3
	v_mov_b32_e32 v6, v0
	v_pk_mul_f32 v[0:1], v[4:5], v[16:17]
	v_max_f32_e32 v5, v9, v9
	v_pk_fma_f32 v[0:1], v[2:3], v[6:7], v[0:1]
	v_max_f32_e32 v3, v8, v8
	v_pk_add_f32 v[78:79], v[78:79], v[0:1]
	v_add_u32_e32 v0, 0x10600, v96
	v_max_f32_e32 v4, 0, v3
	v_add_u32_e32 v3, 0x10620, v96
	ds_read_b64 v[0:1], v0
	ds_read_b64 v[6:7], v3
	v_max_f32_e32 v2, v24, v24
	v_max_f32_e32 v3, v25, v25
	v_max_f32_e32 v5, 0, v5
	v_max_f32_e32 v2, 0, v2
	s_waitcnt lgkmcnt(0)
	v_mov_b32_e32 v9, v6
	v_mov_b32_e32 v6, v1
	v_max_f32_e32 v3, 0, v3
	v_mov_b32_e32 v8, v0
	v_pk_mul_f32 v[0:1], v[4:5], v[6:7]
	v_max_f32_e32 v5, v11, v11
	v_pk_fma_f32 v[0:1], v[2:3], v[8:9], v[0:1]
	v_max_f32_e32 v3, v10, v10
	v_pk_add_f32 v[76:77], v[76:77], v[0:1]
	v_add_u32_e32 v0, 0x10640, v96
	v_max_f32_e32 v4, 0, v3
	v_add_u32_e32 v3, 0x10660, v96
	ds_read_b64 v[0:1], v0
	ds_read_b64 v[6:7], v3
	v_max_f32_e32 v2, v26, v26
	v_max_f32_e32 v3, v27, v27
	v_max_f32_e32 v5, 0, v5
	v_max_f32_e32 v2, 0, v2
	s_waitcnt lgkmcnt(0)
	v_mov_b32_e32 v9, v6
	v_mov_b32_e32 v6, v1
	v_max_f32_e32 v3, 0, v3
	v_mov_b32_e32 v8, v0
	v_pk_mul_f32 v[0:1], v[4:5], v[6:7]
	v_max_f32_e32 v5, v13, v13
	v_pk_fma_f32 v[0:1], v[2:3], v[8:9], v[0:1]
	v_max_f32_e32 v3, v12, v12
	v_pk_add_f32 v[74:75], v[74:75], v[0:1]
	v_add_u32_e32 v0, 0x10700, v96
	v_max_f32_e32 v4, 0, v3
	v_add_u32_e32 v3, 0x10720, v96
	ds_read_b64 v[0:1], v0
	ds_read_b64 v[6:7], v3
	v_max_f32_e32 v2, v28, v28
	v_max_f32_e32 v3, v29, v29
	v_max_f32_e32 v5, 0, v5
	v_max_f32_e32 v2, 0, v2
	s_waitcnt lgkmcnt(0)
	v_mov_b32_e32 v9, v6
	v_mov_b32_e32 v6, v1
	v_max_f32_e32 v3, 0, v3
	v_mov_b32_e32 v8, v0
	v_pk_mul_f32 v[0:1], v[4:5], v[6:7]
	s_nop 0
	v_pk_fma_f32 v[0:1], v[2:3], v[8:9], v[0:1]
	v_max_f32_e32 v2, v30, v30
	v_pk_add_f32 v[72:73], v[72:73], v[0:1]
	v_add_u32_e32 v0, 0x10740, v96
	ds_read_b64 v[0:1], v0
	v_max_f32_e32 v2, 0, v2
	s_waitcnt lgkmcnt(0)
	v_mul_f32_e32 v0, v2, v0
	v_max_f32_e32 v2, v14, v14
	v_max_f32_e32 v2, 0, v2
	v_mul_f32_e32 v2, v2, v1
	v_add_u32_e32 v1, 0x10760, v96
	ds_read_b64 v[4:5], v1
	v_max_f32_e32 v1, v31, v31
	v_max_f32_e32 v6, 0, v1
	v_max_f32_e32 v1, v15, v15
	v_max_f32_e32 v7, 0, v1
	s_waitcnt lgkmcnt(0)
	v_pk_mul_f32 v[4:5], v[6:7], v[4:5]
	s_nop 0
	v_mov_b32_e32 v1, v4
	v_mov_b32_e32 v3, v5
	v_pk_add_f32 v[0:1], v[0:1], v[2:3]
	s_nop 0
	v_pk_add_f32 v[70:71], v[70:71], v[0:1]
	s_cbranch_scc0 .LBB0_872
; __device__ __forceinline__ void score_item(const Frame& F, int l, int samp, int b, int c, int kc) {
;     ...
; #pragma unroll
;             for (int i = 0; i < 16; ++i) { const int q = 32 * qh + (i & 3) + 8 * (i >> 2) + 4 * h; __hip_atomic_store(SC + (size_t)q * 4096 + key, __float_as_uint(sc[i]), __ATOMIC_RELAXED, __HIP_MEMORY_SCOPE_AGENT); }
	v_add_u32_e32 v0, s7, v87
	v_or_b32_e32 v4, 1, v0
	v_ashrrev_i32_e32 v1, 31, v0
	v_ashrrev_i32_e32 v5, 31, v4
	v_lshlrev_b64 v[2:3], 14, v[0:1]
	v_lshlrev_b64 v[4:5], 14, v[4:5]
	v_lshl_add_u64 v[2:3], v[68:69], 0, v[2:3]
	v_lshl_add_u64 v[4:5], v[68:69], 0, v[4:5]
	global_store_dword v[2:3], v84, off sc1
	global_store_dword v[4:5], v85, off sc1
	v_or_b32_e32 v4, 2, v0
	v_or_b32_e32 v0, 3, v0
	v_ashrrev_i32_e32 v5, 31, v4
	v_ashrrev_i32_e32 v1, 31, v0
	v_lshlrev_b64 v[4:5], 14, v[4:5]
	v_lshlrev_b64 v[0:1], 14, v[0:1]
	v_lshl_add_u64 v[4:5], v[68:69], 0, v[4:5]
	v_lshl_add_u64 v[0:1], v[68:69], 0, v[0:1]
	global_store_dword v[4:5], v82, off sc1
	global_store_dword v[0:1], v83, off sc1
	v_add_co_u32_e32 v0, vcc, s92, v2
	s_mov_b32 s18, 1
	s_nop 0
	v_addc_co_u32_e32 v1, vcc, 0, v3, vcc
	global_store_dword v[0:1], v80, off sc1
	v_add_co_u32_e32 v0, vcc, s77, v2
	s_mov_b64 s[14:15], 0
	s_nop 0
	v_addc_co_u32_e32 v1, vcc, 0, v3, vcc
	global_store_dword v[0:1], v81, off sc1
	v_add_co_u32_e32 v0, vcc, s76, v2
	s_nop 1
	v_addc_co_u32_e32 v1, vcc, 0, v3, vcc
	global_store_dword v[0:1], v78, off sc1
	v_add_co_u32_e32 v0, vcc, s78, v2
	s_nop 1
	v_addc_co_u32_e32 v1, vcc, 0, v3, vcc
	global_store_dword v[0:1], v79, off sc1
	v_add_co_u32_e32 v0, vcc, s82, v2
	s_nop 1
	v_addc_co_u32_e32 v1, vcc, 0, v3, vcc
	global_store_dword v[0:1], v76, off sc1
	v_add_co_u32_e32 v0, vcc, s31, v2
	s_nop 1
	v_addc_co_u32_e32 v1, vcc, 0, v3, vcc
	global_store_dword v[0:1], v77, off sc1
	v_add_co_u32_e32 v0, vcc, s84, v2
	s_nop 1
	v_addc_co_u32_e32 v1, vcc, 0, v3, vcc
	global_store_dword v[0:1], v74, off sc1
	v_add_co_u32_e32 v0, vcc, 0x4c000, v2
	s_nop 1
	v_addc_co_u32_e32 v1, vcc, 0, v3, vcc
	global_store_dword v[0:1], v75, off sc1
	v_add_co_u32_e32 v0, vcc, s83, v2
	s_nop 1
	v_addc_co_u32_e32 v1, vcc, 0, v3, vcc
	global_store_dword v[0:1], v72, off sc1
	v_add_co_u32_e32 v0, vcc, 0x64000, v2
	s_nop 1
	v_addc_co_u32_e32 v1, vcc, 0, v3, vcc
	global_store_dword v[0:1], v73, off sc1
	v_add_co_u32_e32 v0, vcc, 0x68000, v2
	s_nop 1
	v_addc_co_u32_e32 v1, vcc, 0, v3, vcc
	global_store_dword v[0:1], v70, off sc1
	v_add_co_u32_e32 v0, vcc, 0x6c000, v2
	s_nop 1
	v_addc_co_u32_e32 v1, vcc, 0, v3, vcc
	s_and_b64 vcc, exec, s[12:13]
	global_store_dword v[0:1], v71, off sc1
	s_cbranch_vccz .LBB0_871

; #define LAS __attribute__((address_space(3)))
; __device__ __forceinline__ void score_item(const Frame& F, int l, int samp, int b, int c, int kc) {
;     ...
;             for (int hh = 0; hh < 8; hh += 2) {
;                 f32x16 s0, s1;
; #pragma unroll
;                 for (int i = 0; i < 16; ++i) { s0[i] = 0.f; s1[i] = 0.f; }
; #pragma unroll
;                 for (int ks = 0; ks < 4; ++ks) { const LAS unsigned char* ap = QiL + (32 * qh + rl) * 1040 + (hh * 64 + 16 * ks + 8 * h) * 2;
;                     const bf16x8 a0 = *(const LAS bf16x8*)(ap), a1 = *(const LAS bf16x8*)(ap + 128);
;                     s0 = __builtin_amdgcn_mfma_f32_32x32x16_bf16(a0, bfr[ks], s0, 0, 0, 0); s1 = __builtin_amdgcn_mfma_f32_32x32x16_bf16(a1, bfr[ks], s1, 0, 0, 0); }
; #pragma unroll
;                 for (int i = 0; i < 16; ++i) { const int q = 32 * qh + (i & 3) + 8 * (i >> 2) + 4 * h; const f32x2 w2 = *(const LAS f32x2*)(WIl + q * 8 + hh); sc[i] += w2[0] * fmaxf(s0[i], 0.f) + w2[1] * fmaxf(s1[i], 0.f); }
;             }
.LBB0_877:
	v_add_u32_e32 v78, 0, v69
	ds_read_b128 v[0:3], v78 offset:128
	ds_read_b128 v[4:7], v78
	ds_read_b128 v[70:73], v78 offset:32
	ds_read_b128 v[74:77], v78 offset:160
	ds_read_b128 v[126:129], v78 offset:64
	ds_read_b128 v[130:133], v78 offset:192
	ds_read_b128 v[134:137], v78 offset:96
	ds_read_b128 v[138:141], v78 offset:224
	s_add_i32 s10, s10, 2
	v_add_u32_e32 v69, 0x100, v69
	s_waitcnt lgkmcnt(6)
	v_mfma_f32_32x32x16_bf16 v[16:31], v[4:7], v[44:47], 0
	s_cmp_lt_u32 s10, 6
	v_mfma_f32_32x32x16_bf16 v[0:15], v[0:3], v[44:47], 0
	s_waitcnt lgkmcnt(4)
	v_mfma_f32_32x32x16_bf16 v[0:15], v[74:77], v[40:43], v[0:15]
	v_mfma_f32_32x32x16_bf16 v[16:31], v[70:73], v[40:43], v[16:31]
	s_waitcnt lgkmcnt(2)
	v_mfma_f32_32x32x16_bf16 v[0:15], v[130:133], v[36:39], v[0:15]
	v_mfma_f32_32x32x16_bf16 v[16:31], v[126:129], v[36:39], v[16:31]
	s_waitcnt lgkmcnt(0)
	v_mfma_f32_32x32x16_bf16 v[0:15], v[138:141], v[32:35], v[0:15]
	v_add_u32_e32 v76, 0, v68
	v_add_u32_e32 v68, 8, v68
	v_mfma_f32_32x32x16_bf16 v[16:31], v[134:137], v[32:35], v[16:31]
	v_add_u32_e32 v70, 0x10400, v76
	v_add_u32_e32 v72, 0x10420, v76
	ds_read_b64 v[70:71], v70
	ds_read_b64 v[72:73], v72
	s_nop 4
	v_max_f32_e32 v0, v0, v0
	v_max_f32_e32 v1, v1, v1
	v_max_f32_e32 v0, 0, v0
	v_max_f32_e32 v16, v16, v16
	v_max_f32_e32 v17, v17, v17
	v_max_f32_e32 v1, 0, v1
	s_waitcnt lgkmcnt(0)
	v_mov_b32_e32 v75, v72
	v_mov_b32_e32 v72, v71
	v_max_f32_e32 v16, 0, v16
	v_max_f32_e32 v17, 0, v17
	v_mov_b32_e32 v74, v70
	v_pk_mul_f32 v[0:1], v[0:1], v[72:73]
	v_max_f32_e32 v2, v2, v2
	v_pk_fma_f32 v[0:1], v[16:17], v[74:75], v[0:1]
	v_add_u32_e32 v17, 0x10460, v76
	v_pk_add_f32 v[66:67], v[66:67], v[0:1]
	v_add_u32_e32 v0, 0x10440, v76
	ds_read_b64 v[0:1], v0
	ds_read_b64 v[70:71], v17
	v_max_f32_e32 v3, v3, v3
	v_max_f32_e32 v16, v18, v18
	v_max_f32_e32 v2, 0, v2
	v_max_f32_e32 v17, v19, v19
	v_max_f32_e32 v3, 0, v3
	s_waitcnt lgkmcnt(0)
	v_mov_b32_e32 v19, v70
	v_mov_b32_e32 v70, v1
	v_max_f32_e32 v16, 0, v16
	v_max_f32_e32 v17, 0, v17
	v_mov_b32_e32 v18, v0
	v_pk_mul_f32 v[0:1], v[2:3], v[70:71]
	v_max_f32_e32 v3, v4, v4
	v_pk_fma_f32 v[0:1], v[16:17], v[18:19], v[0:1]
	v_max_f32_e32 v4, 0, v3
	v_pk_add_f32 v[62:63], v[62:63], v[0:1]
	v_add_u32_e32 v0, 0x10500, v76
	v_add_u32_e32 v3, 0x10520, v76
	ds_read_b64 v[0:1], v0
	ds_read_b64 v[16:17], v3
	v_max_f32_e32 v5, v5, v5
	v_max_f32_e32 v2, v20, v20
	v_max_f32_e32 v3, v21, v21
	v_max_f32_e32 v5, 0, v5
	s_waitcnt lgkmcnt(0)
	v_mov_b32_e32 v19, v16
	v_mov_b32_e32 v16, v1
	v_max_f32_e32 v2, 0, v2
	v_max_f32_e32 v3, 0, v3
	v_mov_b32_e32 v18, v0
	v_pk_mul_f32 v[0:1], v[4:5], v[16:17]
	v_max_f32_e32 v5, v7, v7
	v_pk_fma_f32 v[0:1], v[2:3], v[18:19], v[0:1]
	v_max_f32_e32 v3, v6, v6
	v_pk_add_f32 v[60:61], v[60:61], v[0:1]
	v_add_u32_e32 v0, 0x10540, v76
	v_max_f32_e32 v4, 0, v3
	v_add_u32_e32 v3, 0x10560, v76
	ds_read_b64 v[0:1], v0
	ds_read_b64 v[16:17], v3
	v_max_f32_e32 v2, v22, v22
	v_max_f32_e32 v3, v23, v23
	v_max_f32_e32 v5, 0, v5
	v_max_f32_e32 v2, 0, v2
	s_waitcnt lgkmcnt(0)
	v_mov_b32_e32 v7, v16
	v_mov_b32_e32 v16, v1
	v_max_f32_e32 v3, 0, v3
	v_mov_b32_e32 v6, v0
	v_pk_mul_f32 v[0:1], v[4:5], v[16:17]
	v_max_f32_e32 v5, v9, v9
	v_pk_fma_f32 v[0:1], v[2:3], v[6:7], v[0:1]
	v_max_f32_e32 v3, v8, v8
	v_pk_add_f32 v[58:59], v[58:59], v[0:1]
	v_add_u32_e32 v0, 0x10600, v76
	v_max_f32_e32 v4, 0, v3
	v_add_u32_e32 v3, 0x10620, v76
	ds_read_b64 v[0:1], v0
	ds_read_b64 v[6:7], v3
	v_max_f32_e32 v2, v24, v24
	v_max_f32_e32 v3, v25, v25
	v_max_f32_e32 v5, 0, v5
	v_max_f32_e32 v2, 0, v2
	s_waitcnt lgkmcnt(0)
	v_mov_b32_e32 v9, v6
	v_mov_b32_e32 v6, v1
	v_max_f32_e32 v3, 0, v3
	v_mov_b32_e32 v8, v0
	v_pk_mul_f32 v[0:1], v[4:5], v[6:7]
	v_max_f32_e32 v5, v11, v11
	v_pk_fma_f32 v[0:1], v[2:3], v[8:9], v[0:1]
	v_max_f32_e32 v3, v10, v10
	v_pk_add_f32 v[56:57], v[56:57], v[0:1]
	v_add_u32_e32 v0, 0x10640, v76
	v_max_f32_e32 v4, 0, v3
	v_add_u32_e32 v3, 0x10660, v76
	ds_read_b64 v[0:1], v0
	ds_read_b64 v[6:7], v3
	v_max_f32_e32 v2, v26, v26
	v_max_f32_e32 v3, v27, v27
	v_max_f32_e32 v5, 0, v5
	v_max_f32_e32 v2, 0, v2
	s_waitcnt lgkmcnt(0)
	v_mov_b32_e32 v9, v6
	v_mov_b32_e32 v6, v1
	v_max_f32_e32 v3, 0, v3
	v_mov_b32_e32 v8, v0
	v_pk_mul_f32 v[0:1], v[4:5], v[6:7]
	v_max_f32_e32 v5, v13, v13
	v_pk_fma_f32 v[0:1], v[2:3], v[8:9], v[0:1]
	v_max_f32_e32 v3, v12, v12
	v_pk_add_f32 v[54:55], v[54:55], v[0:1]
	v_add_u32_e32 v0, 0x10700, v76
	v_max_f32_e32 v4, 0, v3
	v_add_u32_e32 v3, 0x10720, v76
	ds_read_b64 v[0:1], v0
	ds_read_b64 v[6:7], v3
	v_max_f32_e32 v2, v28, v28
	v_max_f32_e32 v3, v29, v29
	v_max_f32_e32 v5, 0, v5
	v_max_f32_e32 v2, 0, v2
	s_waitcnt lgkmcnt(0)
	v_mov_b32_e32 v9, v6
	v_mov_b32_e32 v6, v1
	v_max_f32_e32 v3, 0, v3
	v_mov_b32_e32 v8, v0
	v_pk_mul_f32 v[0:1], v[4:5], v[6:7]
	s_nop 0
	v_pk_fma_f32 v[0:1], v[2:3], v[8:9], v[0:1]
	v_max_f32_e32 v2, v30, v30
	v_pk_add_f32 v[52:53], v[52:53], v[0:1]
	v_add_u32_e32 v0, 0x10740, v76
	ds_read_b64 v[0:1], v0
	v_max_f32_e32 v2, 0, v2
	s_waitcnt lgkmcnt(0)
	v_mul_f32_e32 v0, v2, v0
	v_max_f32_e32 v2, v14, v14
	v_max_f32_e32 v2, 0, v2
	v_mul_f32_e32 v2, v2, v1
	v_add_u32_e32 v1, 0x10760, v76
	ds_read_b64 v[4:5], v1
	v_max_f32_e32 v1, v31, v31
	v_max_f32_e32 v6, 0, v1
	v_max_f32_e32 v1, v15, v15
	v_max_f32_e32 v7, 0, v1
	s_waitcnt lgkmcnt(0)
	v_pk_mul_f32 v[4:5], v[6:7], v[4:5]
	s_nop 0
	v_mov_b32_e32 v1, v4
	v_mov_b32_e32 v3, v5
	v_pk_add_f32 v[0:1], v[0:1], v[2:3]
	s_nop 0
	v_pk_add_f32 v[50:51], v[50:51], v[0:1]
	s_cbranch_scc1 .LBB0_877
; __device__ __forceinline__ void score_item(const Frame& F, int l, int samp, int b, int c, int kc) {
;     ...
; #pragma unroll
;             for (int i = 0; i < 16; ++i) { const int q = 32 * qh + (i & 3) + 8 * (i >> 2) + 4 * h; __hip_atomic_store(SC + (size_t)q * 4096 + key, __float_as_uint(sc[i]), __ATOMIC_RELAXED, __HIP_MEMORY_SCOPE_AGENT); }
	v_add_u32_e32 v0, s7, v87
	v_or_b32_e32 v4, 1, v0
	v_ashrrev_i32_e32 v1, 31, v0
	v_ashrrev_i32_e32 v5, 31, v4
	v_lshlrev_b64 v[2:3], 14, v[0:1]
	v_lshlrev_b64 v[4:5], 14, v[4:5]
	v_lshl_add_u64 v[2:3], v[48:49], 0, v[2:3]
	v_lshl_add_u64 v[4:5], v[48:49], 0, v[4:5]
	global_store_dword v[2:3], v66, off sc1
	global_store_dword v[4:5], v67, off sc1
	v_or_b32_e32 v4, 2, v0
	v_or_b32_e32 v0, 3, v0
	v_ashrrev_i32_e32 v5, 31, v4
	v_ashrrev_i32_e32 v1, 31, v0
	v_lshlrev_b64 v[4:5], 14, v[4:5]
	v_lshlrev_b64 v[0:1], 14, v[0:1]
	v_lshl_add_u64 v[4:5], v[48:49], 0, v[4:5]
	v_lshl_add_u64 v[0:1], v[48:49], 0, v[0:1]
	global_store_dword v[4:5], v62, off sc1
	global_store_dword v[0:1], v63, off sc1
	v_add_co_u32_e32 v0, vcc, s92, v2
	s_mov_b32 s10, 1
	s_nop 0
	v_addc_co_u32_e32 v1, vcc, 0, v3, vcc
	global_store_dword v[0:1], v60, off sc1
	v_add_co_u32_e32 v0, vcc, s77, v2
	s_nop 1
	v_addc_co_u32_e32 v1, vcc, 0, v3, vcc
	global_store_dword v[0:1], v61, off sc1
	v_add_co_u32_e32 v0, vcc, s76, v2
	s_nop 1
	v_addc_co_u32_e32 v1, vcc, 0, v3, vcc
	global_store_dword v[0:1], v58, off sc1
	v_add_co_u32_e32 v0, vcc, s78, v2
	s_nop 1
	v_addc_co_u32_e32 v1, vcc, 0, v3, vcc
	global_store_dword v[0:1], v59, off sc1
	v_add_co_u32_e32 v0, vcc, s82, v2
	s_nop 1
	v_addc_co_u32_e32 v1, vcc, 0, v3, vcc
	global_store_dword v[0:1], v56, off sc1
	v_add_co_u32_e32 v0, vcc, s31, v2
	s_nop 1
	v_addc_co_u32_e32 v1, vcc, 0, v3, vcc
	global_store_dword v[0:1], v57, off sc1
	v_add_co_u32_e32 v0, vcc, s84, v2
	s_nop 1
	v_addc_co_u32_e32 v1, vcc, 0, v3, vcc
	global_store_dword v[0:1], v54, off sc1
	v_add_co_u32_e32 v0, vcc, 0x4c000, v2
	s_nop 1
	v_addc_co_u32_e32 v1, vcc, 0, v3, vcc
	global_store_dword v[0:1], v55, off sc1
	v_add_co_u32_e32 v0, vcc, s83, v2
	s_nop 1
	v_addc_co_u32_e32 v1, vcc, 0, v3, vcc
	global_store_dword v[0:1], v52, off sc1
	v_add_co_u32_e32 v0, vcc, 0x64000, v2
	s_nop 1
	v_addc_co_u32_e32 v1, vcc, 0, v3, vcc
	global_store_dword v[0:1], v53, off sc1
	v_add_co_u32_e32 v0, vcc, 0x68000, v2
	s_nop 1
	v_addc_co_u32_e32 v1, vcc, 0, v3, vcc
	global_store_dword v[0:1], v50, off sc1
	v_add_co_u32_e32 v0, vcc, 0x6c000, v2
	s_nop 1
	v_addc_co_u32_e32 v1, vcc, 0, v3, vcc
	s_andn2_b64 vcc, exec, s[8:9]
	s_mov_b64 s[8:9], 0
	global_store_dword v[0:1], v51, off sc1
	s_cbranch_vccnz .LBB0_876
